# diff item epilogue: the 7 serialized subln-gamma loads (load, wait vmcnt(0), use) hoisted into dead S-tile registers and issued together
# baseline (speedup 1.0000x reference)
; DI void phase_diff(KP p, int layer, u16* sm) {
;     ...
;     const int lsrc = (r & 15) + ((r >> 4) << 5);
;     const float l0 = __shfl(L4[0][0], lsrc), l1 = __shfl(L4[1][0], lsrc);
;     const float i0 = 1.f / l0, i1 = lam / l1;
;     float ss = 0.f;
; #pragma unroll
;     for (int mb = 0; mb < 2; ++mb)
; #pragma unroll
;       for (int i = 0; i < 16; ++i) { const float v = O[0][mb][i] * i0 - O[1][mb][i] * i1; O[0][mb][i] = v; ss += v * v; }
;     ss += __shfl_xor(ss, 32);
;     const float inv = rsqrtf(ss * (1.f / 64.f) + 1e-6f) * (1.f - lam_init);
;     u16* op = p.o + (size_t)(b * S + tq) * 1024 + head * 64;
; #pragma unroll
;     for (int mb = 0; mb < 2; ++mb)
; #pragma unroll
;       for (int g = 0; g < 4; ++g) {
;         const int d = mb * 32 + 8 * g + 4 * hh;
;         const float4 g4 = *(const float4*)(sg + d);
.LBB0_462:
	s_setprio 0
	s_nop 7
	ds_bpermute_b32 v10, v238, v196
	ds_bpermute_b32 v11, v238, v200
	s_mov_b32 s31, s13
	s_add_i32 s36, s36, s74
	s_cmpk_lt_i32 s36, 0x200
	s_waitcnt lgkmcnt(1)
	v_div_scale_f32 v12, s[6:7], v10, v10, 1.0
	v_rcp_f32_e32 v13, v12
	s_nop 0
	v_fma_f32 v80, -v12, v13, 1.0
	v_fmac_f32_e32 v13, v80, v13
	v_div_scale_f32 v80, vcc, 1.0, v10, 1.0
	v_mul_f32_e32 v81, v80, v13
	v_fma_f32 v82, -v12, v81, v80
	v_fmac_f32_e32 v81, v82, v13
	v_fma_f32 v12, -v12, v81, v80
	v_div_fmas_f32 v12, v12, v13, v81
	v_div_fixup_f32 v80, v12, v10, 1.0
	s_waitcnt lgkmcnt(0)
	v_div_scale_f32 v10, s[6:7], v11, v11, v248
	v_rcp_f32_e32 v12, v10
	s_nop 0
	v_fma_f32 v13, -v10, v12, 1.0
	v_fmac_f32_e32 v12, v13, v12
	v_div_scale_f32 v13, vcc, v248, v11, v248
	v_mul_f32_e32 v81, v13, v12
	v_fma_f32 v82, -v10, v81, v13
	v_fmac_f32_e32 v81, v82, v12
	v_fma_f32 v10, -v10, v81, v13
	v_div_fmas_f32 v10, v10, v12, v81
	v_div_fixup_f32 v82, v10, v11, v248
	v_pk_mul_f32 v[10:11], v[44:45], v[82:83] op_sel_hi:[1,0]
	v_pk_mul_f32 v[12:13], v[46:47], v[82:83] op_sel_hi:[1,0]
	v_pk_fma_f32 v[10:11], v[60:61], v[80:81], v[10:11] op_sel_hi:[1,0,1] neg_lo:[0,0,1] neg_hi:[0,0,1]
	v_pk_mul_f32 v[60:61], v[66:67], v[82:83] op_sel_hi:[1,0]
	v_pk_fma_f32 v[12:13], v[62:63], v[80:81], v[12:13] op_sel_hi:[1,0,1] neg_lo:[0,0,1] neg_hi:[0,0,1]
	v_pk_fma_f32 v[66:67], v[98:99], v[80:81], v[60:61] op_sel_hi:[1,0,1] neg_lo:[0,0,1] neg_hi:[0,0,1]
	global_load_dwordx4 v[60:63], v[208:209], off
	global_load_dwordx4 v[112:115], v[208:209], off offset:32
	global_load_dwordx4 v[116:119], v[208:209], off offset:64
	global_load_dwordx4 v[120:123], v[208:209], off offset:96
	global_load_dwordx4 v[124:127], v[208:209], off offset:128
	global_load_dwordx4 v[128:131], v[208:209], off offset:160
	global_load_dwordx4 v[132:135], v[208:209], off offset:192
	global_load_dwordx4 v[136:139], v[208:209], off offset:224
	v_pk_mul_f32 v[64:65], v[64:65], v[82:83] op_sel_hi:[1,0]
	v_pk_mul_f32 v[70:71], v[70:71], v[82:83] op_sel_hi:[1,0]
	v_pk_fma_f32 v[64:65], v[96:97], v[80:81], v[64:65] op_sel_hi:[1,0,1] neg_lo:[0,0,1] neg_hi:[0,0,1]
	v_pk_mul_f32 v[68:69], v[68:69], v[82:83] op_sel_hi:[1,0]
	v_pk_mul_f32 v[88:89], v[64:65], v[64:65]
	v_pk_mul_f32 v[74:75], v[74:75], v[82:83] op_sel_hi:[1,0]
	v_pk_mul_f32 v[72:73], v[72:73], v[82:83] op_sel_hi:[1,0]
	v_pk_mul_f32 v[78:79], v[78:79], v[82:83] op_sel_hi:[1,0]
	v_pk_mul_f32 v[76:77], v[76:77], v[82:83] op_sel_hi:[1,0]
	v_pk_mul_f32 v[34:35], v[34:35], v[82:83] op_sel_hi:[1,0]
	v_pk_mul_f32 v[32:33], v[32:33], v[82:83] op_sel_hi:[1,0]
	v_pk_mul_f32 v[38:39], v[38:39], v[82:83] op_sel_hi:[1,0]
	v_pk_mul_f32 v[36:37], v[36:37], v[82:83] op_sel_hi:[1,0]
	v_pk_mul_f32 v[42:43], v[42:43], v[82:83] op_sel_hi:[1,0]
	v_pk_mul_f32 v[40:41], v[40:41], v[82:83] op_sel_hi:[1,0]
	v_pk_mul_f32 v[86:87], v[66:67], v[66:67]
	v_pk_fma_f32 v[70:71], v[102:103], v[80:81], v[70:71] op_sel_hi:[1,0,1] neg_lo:[0,0,1] neg_hi:[0,0,1]
	v_pk_fma_f32 v[68:69], v[100:101], v[80:81], v[68:69] op_sel_hi:[1,0,1] neg_lo:[0,0,1] neg_hi:[0,0,1]
	v_pk_fma_f32 v[74:75], v[106:107], v[80:81], v[74:75] op_sel_hi:[1,0,1] neg_lo:[0,0,1] neg_hi:[0,0,1]
	v_pk_fma_f32 v[72:73], v[104:105], v[80:81], v[72:73] op_sel_hi:[1,0,1] neg_lo:[0,0,1] neg_hi:[0,0,1]
	v_pk_fma_f32 v[78:79], v[110:111], v[80:81], v[78:79] op_sel_hi:[1,0,1] neg_lo:[0,0,1] neg_hi:[0,0,1]
	v_pk_fma_f32 v[76:77], v[108:109], v[80:81], v[76:77] op_sel_hi:[1,0,1] neg_lo:[0,0,1] neg_hi:[0,0,1]
	v_pk_fma_f32 v[50:51], v[50:51], v[80:81], v[34:35] op_sel_hi:[1,0,1] neg_lo:[0,0,1] neg_hi:[0,0,1]
	v_pk_fma_f32 v[48:49], v[48:49], v[80:81], v[32:33] op_sel_hi:[1,0,1] neg_lo:[0,0,1] neg_hi:[0,0,1]
	v_pk_fma_f32 v[38:39], v[54:55], v[80:81], v[38:39] op_sel_hi:[1,0,1] neg_lo:[0,0,1] neg_hi:[0,0,1]
	v_pk_fma_f32 v[36:37], v[52:53], v[80:81], v[36:37] op_sel_hi:[1,0,1] neg_lo:[0,0,1] neg_hi:[0,0,1]
	v_pk_fma_f32 v[42:43], v[58:59], v[80:81], v[42:43] op_sel_hi:[1,0,1] neg_lo:[0,0,1] neg_hi:[0,0,1]
	v_pk_fma_f32 v[40:41], v[56:57], v[80:81], v[40:41] op_sel_hi:[1,0,1] neg_lo:[0,0,1] neg_hi:[0,0,1]
	v_add_f32_e32 v80, v88, v89
	v_add_f32_e32 v80, v86, v80
	v_pk_mul_f32 v[92:93], v[68:69], v[68:69]
	v_add_f32_e32 v80, v87, v80
	v_add_f32_e32 v80, v92, v80
	v_pk_mul_f32 v[90:91], v[70:71], v[70:71]
	v_add_f32_e32 v80, v93, v80
	v_add_f32_e32 v80, v90, v80
	v_pk_mul_f32 v[96:97], v[72:73], v[72:73]
	v_add_f32_e32 v80, v91, v80
	v_add_f32_e32 v80, v96, v80
	v_pk_mul_f32 v[94:95], v[74:75], v[74:75]
	v_add_f32_e32 v80, v97, v80
	v_add_f32_e32 v80, v94, v80
	v_pk_mul_f32 v[100:101], v[76:77], v[76:77]
	v_add_f32_e32 v80, v95, v80
	v_add_f32_e32 v80, v100, v80
	v_pk_mul_f32 v[98:99], v[78:79], v[78:79]
	v_add_f32_e32 v80, v101, v80
	v_add_f32_e32 v80, v98, v80
	v_pk_mul_f32 v[32:33], v[48:49], v[48:49]
	v_add_f32_e32 v80, v99, v80
	v_add_f32_e32 v32, v32, v80
	v_pk_mul_f32 v[34:35], v[50:51], v[50:51]
	v_add_f32_e32 v32, v33, v32
	v_add_f32_e32 v32, v34, v32
	v_pk_mul_f32 v[52:53], v[36:37], v[36:37]
	v_add_f32_e32 v32, v35, v32
	v_add_f32_e32 v32, v52, v32
	v_pk_mul_f32 v[54:55], v[38:39], v[38:39]
	v_add_f32_e32 v32, v53, v32
	v_add_f32_e32 v32, v54, v32
	v_pk_mul_f32 v[56:57], v[40:41], v[40:41]
	v_add_f32_e32 v32, v55, v32
	v_add_f32_e32 v32, v56, v32
	v_pk_mul_f32 v[58:59], v[42:43], v[42:43]
	v_add_f32_e32 v32, v57, v32
	v_add_f32_e32 v32, v58, v32
	v_pk_mul_f32 v[84:85], v[10:11], v[10:11]
	v_add_f32_e32 v32, v59, v32
	v_add_f32_e32 v32, v84, v32
	v_pk_mul_f32 v[46:47], v[12:13], v[12:13]
	v_add_f32_e32 v32, v85, v32
	v_add_f32_e32 v32, v46, v32
	v_add_f32_e32 v32, v47, v32
	ds_bpermute_b32 v33, v242, v32
	v_lshl_add_u32 v44, s37, 14, v215
	v_ashrrev_i32_e32 v45, 31, v44
	v_lshlrev_b64 v[44:45], 11, v[44:45]
	v_lshl_add_u64 v[44:45], s[44:45], 0, v[44:45]
	s_waitcnt lgkmcnt(0)
; DI unsigned pack2(float a, float b) { f2_t v = {a, b}; return __builtin_bit_cast(unsigned, __builtin_convertvector(v, bf2_t)); }
; DI void phase_diff(KP p, int layer, u16* sm) {
;     ...
;     ss += __shfl_xor(ss, 32);
;     const float inv = rsqrtf(ss * (1.f / 64.f) + 1e-6f) * (1.f - lam_init);
;     u16* op = p.o + (size_t)(b * S + tq) * 1024 + head * 64;
; #pragma unroll
;     for (int mb = 0; mb < 2; ++mb)
; #pragma unroll
;       for (int g = 0; g < 4; ++g) {
;         const int d = mb * 32 + 8 * g + 4 * hh;
;         const float4 g4 = *(const float4*)(sg + d);
;         *(uint2*)(op + d) = make_uint2(pack2(O[0][mb][4 * g] * inv * g4.x, O[0][mb][4 * g + 1] * inv * g4.y),
;                                        pack2(O[0][mb][4 * g + 2] * inv * g4.z, O[0][mb][4 * g + 3] * inv * g4.w));
;       }
	v_add_f32_e32 v32, v32, v33
	v_fmamk_f32 v32, v32, 0x3c800000, v225
	v_cmp_gt_f32_e32 vcc, s33, v32
	v_mul_f32_e32 v33, 0x4b800000, v32
	v_lshl_add_u64 v[44:45], v[44:45], 0, s[30:31]
	v_cndmask_b32_e32 v32, v32, v33, vcc
	v_rsq_f32_e32 v32, v32
	v_mov_b32_e32 v215, v1
	v_lshl_add_u64 v[44:45], v[44:45], 0, v[214:215]
	v_mul_f32_e32 v33, 0x45800000, v32
	v_cndmask_b32_e32 v32, v32, v33, vcc
	v_mul_f32_e32 v46, v236, v32
	v_pk_mul_f32 v[32:33], v[64:65], v[46:47] op_sel_hi:[1,0]
	v_pk_mul_f32 v[34:35], v[66:67], v[46:47] op_sel_hi:[1,0]
	s_waitcnt vmcnt(0)
	v_pk_mul_f32 v[32:33], v[60:61], v[32:33]
	v_pk_mul_f32 v[34:35], v[62:63], v[34:35]
	v_cvt_pk_bf16_f32 v32, v32, v33
	v_cvt_pk_bf16_f32 v33, v34, v35
	global_store_dwordx2 v[44:45], v[32:33], off
	s_nop 1
	v_pk_mul_f32 v[52:53], v[68:69], v[46:47] op_sel_hi:[1,0]
	v_pk_mul_f32 v[48:49], v[48:49], v[46:47] op_sel_hi:[1,0]
	v_pk_mul_f32 v[36:37], v[36:37], v[46:47] op_sel_hi:[1,0]
	v_pk_mul_f32 v[10:11], v[10:11], v[46:47] op_sel_hi:[1,0]
	v_pk_mul_f32 v[12:13], v[12:13], v[46:47] op_sel_hi:[1,0]
	v_pk_mul_f32 v[32:33], v[112:113], v[52:53]
	v_pk_mul_f32 v[52:53], v[70:71], v[46:47] op_sel_hi:[1,0]
	v_cvt_pk_bf16_f32 v32, v32, v33
	v_pk_mul_f32 v[34:35], v[114:115], v[52:53]
	v_pk_mul_f32 v[52:53], v[72:73], v[46:47] op_sel_hi:[1,0]
	v_cvt_pk_bf16_f32 v33, v34, v35
	global_store_dwordx2 v[44:45], v[32:33], off offset:16
	s_nop 1
	v_pk_mul_f32 v[32:33], v[116:117], v[52:53]
	v_pk_mul_f32 v[52:53], v[74:75], v[46:47] op_sel_hi:[1,0]
	v_cvt_pk_bf16_f32 v32, v32, v33
	v_pk_mul_f32 v[34:35], v[118:119], v[52:53]
	v_pk_mul_f32 v[52:53], v[76:77], v[46:47] op_sel_hi:[1,0]
	v_cvt_pk_bf16_f32 v33, v34, v35
	global_store_dwordx2 v[44:45], v[32:33], off offset:32
	s_nop 1
	v_pk_mul_f32 v[32:33], v[120:121], v[52:53]
	v_pk_mul_f32 v[52:53], v[78:79], v[46:47] op_sel_hi:[1,0]
	v_cvt_pk_bf16_f32 v32, v32, v33
	v_pk_mul_f32 v[34:35], v[122:123], v[52:53]
	s_nop 0
	v_cvt_pk_bf16_f32 v33, v34, v35
	global_store_dwordx2 v[44:45], v[32:33], off offset:48
	s_nop 1
	v_pk_mul_f32 v[32:33], v[124:125], v[48:49]
	v_pk_mul_f32 v[48:49], v[50:51], v[46:47] op_sel_hi:[1,0]
	v_cvt_pk_bf16_f32 v32, v32, v33
	v_pk_mul_f32 v[34:35], v[126:127], v[48:49]
	s_nop 0
	v_cvt_pk_bf16_f32 v33, v34, v35
	global_store_dwordx2 v[44:45], v[32:33], off offset:64
	s_nop 1
	v_pk_mul_f32 v[32:33], v[128:129], v[36:37]
	v_pk_mul_f32 v[36:37], v[38:39], v[46:47] op_sel_hi:[1,0]
	v_cvt_pk_bf16_f32 v32, v32, v33
	v_pk_mul_f32 v[34:35], v[130:131], v[36:37]
	v_pk_mul_f32 v[36:37], v[40:41], v[46:47] op_sel_hi:[1,0]
	v_cvt_pk_bf16_f32 v33, v34, v35
	global_store_dwordx2 v[44:45], v[32:33], off offset:80
	s_nop 1
	v_pk_mul_f32 v[32:33], v[132:133], v[36:37]
	v_pk_mul_f32 v[36:37], v[42:43], v[46:47] op_sel_hi:[1,0]
	v_cvt_pk_bf16_f32 v32, v32, v33
	v_pk_mul_f32 v[34:35], v[134:135], v[36:37]
	s_nop 0
	v_cvt_pk_bf16_f32 v33, v34, v35
	global_store_dwordx2 v[44:45], v[32:33], off offset:96
	s_nop 1
	v_pk_mul_f32 v[10:11], v[136:137], v[10:11]
	v_pk_mul_f32 v[12:13], v[138:139], v[12:13]
	v_cvt_pk_bf16_f32 v10, v10, v11
	v_cvt_pk_bf16_f32 v11, v12, v13
	global_store_dwordx2 v[44:45], v[10:11], off offset:112
	s_nop 1
	s_cbranch_scc0 .LBB0_474
